# packed f32 add/mul in the attention loops split into scalar pairs
# baseline (speedup 1.0000x reference)
.LBB0_295:
	s_nop 8
	v_max3_f32 v124, v33, v49, v34
	v_max3_f32 v125, v50, v35, v51
	v_max3_f32 v126, v48, v32, v36
	v_max3_f32 v127, v52, v37, v53
	v_max3_f32 v124, v124, v38, v54
	v_max3_f32 v125, v125, v39, v55
	v_max3_f32 v126, v126, v40, v56
	v_max3_f32 v127, v127, v41, v57
	v_max3_f32 v124, v124, v42, v58
	v_max3_f32 v125, v125, v43, v59
	v_max3_f32 v126, v126, v44, v60
	v_max3_f32 v127, v127, v45, v61
	v_max3_f32 v124, v124, v46, v62
	v_max3_f32 v125, v125, v47, v63
	v_max3_f32 v124, v124, v125, v126
	v_max_f32_e32 v124, v124, v127
	v_mov_b32_e32 v125, v124
	s_nop 1
	v_permlane32_swap_b32_e32 v125, v124
	s_waitcnt lgkmcnt(0)
	v_max3_f32 v124, v123, v124, v125
	v_sub_f32_e32 v123, v123, v124
	v_exp_f32_e32 v123, v123
	s_nop 0
	v_cmp_eq_f32_e32 vcc, 1.0, v123
	s_cmp_eq_u64 vcc, exec
	s_cbranch_scc1 .LBB0_299
	s_and_saveexec_b64 s[84:85], s[20:21]
	ds_write_b32 v118, v123 offset:32768
	s_or_b64 exec, exec, s[84:85]
	v_add_u32_e32 v125, s96, v98
	ds_read_b128 v[126:129], v125 offset:32864
	ds_read_b128 v[130:133], v125 offset:32832
	ds_read_b128 v[134:137], v125 offset:32800
	ds_read_b128 v[138:141], v125 offset:32768
	s_waitcnt lgkmcnt(3)
	v_mul_f32_e32 v12, v12, v126
	v_mul_f32_e32 v13, v13, v127
	s_waitcnt lgkmcnt(2)
	v_mul_f32_e32 v8, v8, v130
	v_mul_f32_e32 v9, v9, v131
	s_waitcnt lgkmcnt(1)
	v_mul_f32_e32 v4, v4, v134
	v_mul_f32_e32 v5, v5, v135
	v_mul_f32_e32 v14, v14, v128
	v_mul_f32_e32 v15, v15, v129
	v_mul_f32_e32 v10, v10, v132
	v_mul_f32_e32 v11, v11, v133
	v_mul_f32_e32 v6, v6, v136
	v_mul_f32_e32 v7, v7, v137
	s_waitcnt lgkmcnt(0)
	v_mul_f32_e32 v2, v2, v140
	v_mul_f32_e32 v3, v3, v141
	v_mul_f32_e32 v0, v0, v138
	v_mul_f32_e32 v1, v1, v139
	v_mul_f32_e32 v28, v28, v126
	v_mul_f32_e32 v29, v29, v127
	v_mul_f32_e32 v24, v24, v130
	v_mul_f32_e32 v25, v25, v131
	v_mul_f32_e32 v20, v20, v134
	v_mul_f32_e32 v21, v21, v135
	v_mul_f32_e32 v30, v30, v128
	v_mul_f32_e32 v31, v31, v129
	v_mul_f32_e32 v26, v26, v132
	v_mul_f32_e32 v27, v27, v133
	v_mul_f32_e32 v22, v22, v136
	v_mul_f32_e32 v23, v23, v137
	v_mul_f32_e32 v18, v18, v140
	v_mul_f32_e32 v19, v19, v141
	v_mul_f32_e32 v16, v16, v138
	v_mul_f32_e32 v17, v17, v139
.LBB0_299:
	v_sub_f32_e32 v63, v63, v124
	v_sub_f32_e32 v62, v62, v124
	v_sub_f32_e32 v61, v61, v124
	v_sub_f32_e32 v60, v60, v124
	v_sub_f32_e32 v59, v59, v124
	v_sub_f32_e32 v58, v58, v124
	v_sub_f32_e32 v57, v57, v124
	v_sub_f32_e32 v56, v56, v124
	v_sub_f32_e32 v55, v55, v124
	v_sub_f32_e32 v54, v54, v124
	v_sub_f32_e32 v53, v53, v124
	v_sub_f32_e32 v52, v52, v124
	v_sub_f32_e32 v51, v51, v124
	v_sub_f32_e32 v50, v50, v124
	v_sub_f32_e32 v49, v49, v124
	v_sub_f32_e32 v48, v48, v124
	v_sub_f32_e32 v126, v47, v124
	v_sub_f32_e32 v127, v46, v124
	v_sub_f32_e32 v128, v45, v124
	v_sub_f32_e32 v129, v44, v124
	v_sub_f32_e32 v130, v43, v124
	v_sub_f32_e32 v131, v42, v124
	v_sub_f32_e32 v132, v41, v124
	v_sub_f32_e32 v133, v40, v124
	v_sub_f32_e32 v47, v39, v124
	v_sub_f32_e32 v39, v38, v124
	v_sub_f32_e32 v38, v37, v124
	v_sub_f32_e32 v37, v36, v124
	v_sub_f32_e32 v36, v35, v124
	v_sub_f32_e32 v35, v34, v124
	v_sub_f32_e32 v34, v33, v124
	v_sub_f32_e32 v33, v32, v124
	v_exp_f32_e32 v32, v48
	v_exp_f32_e32 v40, v33
	v_exp_f32_e32 v33, v49
	v_exp_f32_e32 v41, v34
	v_exp_f32_e32 v34, v50
	v_exp_f32_e32 v42, v35
	v_exp_f32_e32 v35, v51
	v_exp_f32_e32 v43, v36
	v_exp_f32_e32 v36, v52
	v_exp_f32_e32 v44, v37
	v_exp_f32_e32 v37, v53
	v_exp_f32_e32 v45, v38
	v_exp_f32_e32 v38, v54
	v_exp_f32_e32 v46, v39
	v_exp_f32_e32 v39, v55
	v_exp_f32_e32 v47, v47
	v_exp_f32_e32 v48, v56
	v_exp_f32_e32 v50, v133
	v_exp_f32_e32 v49, v57
	v_exp_f32_e32 v51, v132
	v_exp_f32_e32 v52, v58
	v_exp_f32_e32 v54, v131
	v_exp_f32_e32 v53, v59
	v_exp_f32_e32 v55, v130
	v_exp_f32_e32 v56, v60
	v_exp_f32_e32 v58, v129
	v_exp_f32_e32 v57, v61
	v_exp_f32_e32 v60, v62
	v_exp_f32_e32 v62, v127
	v_exp_f32_e32 v61, v63
	v_exp_f32_e32 v63, v126
	v_exp_f32_e32 v59, v128
	v_add_f32_e32 v126, v52, v54
	v_add_f32_e32 v127, v53, v55
	v_add_f32_e32 v128, v34, v42
	v_add_f32_e32 v129, v35, v43
	v_add_f32_e32 v130, v60, v62
	v_add_f32_e32 v131, v61, v63
	v_add_f32_e32 v132, v38, v46
	v_add_f32_e32 v133, v39, v47
	v_add_f32_e32 v134, v48, v50
	v_add_f32_e32 v135, v49, v51
	v_add_f32_e32 v136, v32, v40
	v_add_f32_e32 v137, v33, v41
	v_add_f32_e32 v138, v56, v58
	v_add_f32_e32 v139, v57, v59
	v_add_f32_e32 v140, v36, v44
	v_add_f32_e32 v141, v37, v45
	v_add_f32_e32 v134, v136, v134
	v_add_f32_e32 v135, v137, v135
	v_add_f32_e32 v138, v140, v138
	v_add_f32_e32 v139, v141, v139
	v_add_f32_e32 v130, v132, v130
	v_add_f32_e32 v131, v133, v131
	v_add_f32_e32 v126, v128, v126
	v_add_f32_e32 v127, v129, v127
	v_add_f32_e32 v128, v134, v138
	v_add_f32_e32 v129, v135, v139
	v_add_f32_e32 v126, v126, v130
	v_add_f32_e32 v127, v127, v131
	v_add_f32_e32 v128, v128, v129
	v_add_f32_e32 v126, v126, v127
	v_add_f32_e32 v126, v128, v126
	v_add_u32_e32 v125, s61, v116
	v_fmac_f32_e32 v126, v122, v123
	v_cvt_pk_bf16_f32 v32, v32, v33
	v_cvt_pk_bf16_f32 v33, v34, v35
	v_cvt_pk_bf16_f32 v34, v36, v37
	v_cvt_pk_bf16_f32 v35, v38, v39
	v_cvt_pk_bf16_f32 v36, v48, v49
	v_cvt_pk_bf16_f32 v37, v52, v53
	v_cvt_pk_bf16_f32 v38, v56, v57
	v_cvt_pk_bf16_f32 v39, v60, v61
	v_cvt_pk_bf16_f32 v40, v40, v41
	v_cvt_pk_bf16_f32 v41, v42, v43
	v_cvt_pk_bf16_f32 v42, v44, v45
	v_cvt_pk_bf16_f32 v43, v46, v47
	v_cvt_pk_bf16_f32 v44, v50, v51
	v_cvt_pk_bf16_f32 v45, v54, v55
	v_cvt_pk_bf16_f32 v46, v58, v59
	v_cvt_pk_bf16_f32 v47, v62, v63
	s_setprio 1
	v_add3_u32 v52, v125, v112, v117
	ds_read_b64_tr_b16 v[216:217], v52 offset:8192
	ds_read_b64_tr_b16 v[218:219], v52 offset:8704
	ds_read_b64_tr_b16 v[220:221], v52 offset:9216
	ds_read_b64_tr_b16 v[222:223], v52 offset:9728
	s_waitcnt lgkmcnt(2)
	v_mfma_f32_32x32x16_bf16 v[0:15], v[32:35], v[216:219], v[0:15]
	ds_read_b64_tr_b16 v[216:217], v52 offset:10240
	ds_read_b64_tr_b16 v[218:219], v52 offset:10752
	s_waitcnt lgkmcnt(2)
	v_mfma_f32_32x32x16_bf16 v[0:15], v[36:39], v[220:223], v[0:15]
	ds_read_b64_tr_b16 v[220:221], v52 offset:11264
	ds_read_b64_tr_b16 v[222:223], v52 offset:11776
	s_waitcnt lgkmcnt(2)
	v_mfma_f32_32x32x16_bf16 v[0:15], v[40:43], v[216:219], v[0:15]
	ds_read_b64_tr_b16 v[216:217], v52 offset:12288
	ds_read_b64_tr_b16 v[218:219], v52 offset:12800
	s_waitcnt lgkmcnt(2)
	v_mfma_f32_32x32x16_bf16 v[0:15], v[44:47], v[220:223], v[0:15]
	ds_read_b64_tr_b16 v[220:221], v52 offset:13312
	ds_read_b64_tr_b16 v[222:223], v52 offset:13824
	s_waitcnt lgkmcnt(2)
	v_mfma_f32_32x32x16_bf16 v[16:31], v[32:35], v[216:219], v[16:31]
	ds_read_b64_tr_b16 v[216:217], v52 offset:14336
	ds_read_b64_tr_b16 v[218:219], v52 offset:14848
	s_waitcnt lgkmcnt(2)
	v_mfma_f32_32x32x16_bf16 v[16:31], v[36:39], v[220:223], v[16:31]
	ds_read_b64_tr_b16 v[220:221], v52 offset:15360
	ds_read_b64_tr_b16 v[222:223], v52 offset:15872
	s_waitcnt lgkmcnt(2)
	v_mfma_f32_32x32x16_bf16 v[16:31], v[40:43], v[216:219], v[16:31]
	s_waitcnt lgkmcnt(0)
	v_mfma_f32_32x32x16_bf16 v[16:31], v[44:47], v[220:223], v[16:31]
	s_setprio 0
	s_mov_b32 s61, 0
	v_mov_b32_e32 v122, v126
	v_mov_b32_e32 v123, v124

.LBB0_3835:
	s_waitcnt lgkmcnt(0)
	v_max3_f32 v38, v52, v47, v53
	v_sub_f32_e32 v39, v52, v38
	v_sub_f32_e32 v33, v33, v38
	v_sub_f32_e32 v32, v32, v38
	v_sub_f32_e32 v31, v31, v38
	v_sub_f32_e32 v30, v30, v38
	v_sub_f32_e32 v29, v29, v38
	v_sub_f32_e32 v28, v28, v38
	v_sub_f32_e32 v27, v27, v38
	v_sub_f32_e32 v26, v26, v38
	v_sub_f32_e32 v25, v25, v38
	v_sub_f32_e32 v24, v24, v38
	v_sub_f32_e32 v23, v23, v38
	v_sub_f32_e32 v22, v22, v38
	v_sub_f32_e32 v21, v21, v38
	v_sub_f32_e32 v20, v20, v38
	v_sub_f32_e32 v19, v19, v38
	v_sub_f32_e32 v18, v18, v38
	v_sub_f32_e32 v40, v17, v38
	v_sub_f32_e32 v41, v16, v38
	v_sub_f32_e32 v47, v15, v38
	v_sub_f32_e32 v52, v14, v38
	v_sub_f32_e32 v53, v13, v38
	v_sub_f32_e32 v54, v12, v38
	v_sub_f32_e32 v55, v11, v38
	v_sub_f32_e32 v56, v10, v38
	v_sub_f32_e32 v17, v9, v38
	v_sub_f32_e32 v15, v8, v38
	v_sub_f32_e32 v13, v7, v38
	v_sub_f32_e32 v11, v6, v38
	v_sub_f32_e32 v9, v5, v38
	v_sub_f32_e32 v7, v4, v38
	v_sub_f32_e32 v5, v3, v38
	v_sub_f32_e32 v3, v2, v38
	v_exp_f32_e32 v2, v18
	v_exp_f32_e32 v4, v3
	v_exp_f32_e32 v3, v19
	v_exp_f32_e32 v5, v5
	v_exp_f32_e32 v6, v20
	v_exp_f32_e32 v8, v7
	v_exp_f32_e32 v7, v21
	v_exp_f32_e32 v9, v9
	v_exp_f32_e32 v10, v22
	v_exp_f32_e32 v12, v11
	v_exp_f32_e32 v11, v23
	v_exp_f32_e32 v13, v13
	v_exp_f32_e32 v14, v24
	v_exp_f32_e32 v16, v15
	v_exp_f32_e32 v15, v25
	v_exp_f32_e32 v17, v17
	v_exp_f32_e32 v18, v26
	v_exp_f32_e32 v20, v56
	v_exp_f32_e32 v19, v27
	v_exp_f32_e32 v21, v55
	v_exp_f32_e32 v22, v28
	v_exp_f32_e32 v24, v54
	v_exp_f32_e32 v23, v29
	v_exp_f32_e32 v25, v53
	v_exp_f32_e32 v26, v30
	v_exp_f32_e32 v28, v52
	v_exp_f32_e32 v27, v31
	v_exp_f32_e32 v29, v47
	v_exp_f32_e32 v30, v32
	v_exp_f32_e32 v32, v41
	v_exp_f32_e32 v31, v33
	v_exp_f32_e32 v33, v40
	v_add_f32_e32 v22, v24, v22
	v_add_f32_e32 v23, v25, v23
	v_add_f32_e32 v6, v8, v6
	v_add_f32_e32 v7, v9, v7
	v_add_f32_e32 v14, v16, v14
	v_add_f32_e32 v15, v17, v15
	v_add_f32_e32 v8, v32, v30
	v_add_f32_e32 v9, v33, v31
	v_add_f32_e32 v16, v20, v18
	v_add_f32_e32 v17, v21, v19
	v_add_f32_e32 v2, v4, v2
	v_add_f32_e32 v3, v5, v3
	v_add_f32_e32 v4, v28, v26
	v_add_f32_e32 v5, v29, v27
	v_add_f32_e32 v10, v12, v10
	v_add_f32_e32 v11, v13, v11
	v_exp_f32_e32 v39, v39
	v_add_f32_e32 v4, v10, v4
	v_add_f32_e32 v5, v11, v5
	v_add_f32_e32 v2, v2, v16
	v_add_f32_e32 v3, v3, v17
	v_add_f32_e32 v8, v14, v8
	v_add_f32_e32 v9, v15, v9
	v_add_f32_e32 v6, v6, v22
	v_add_f32_e32 v7, v7, v23
	v_add_f32_e32 v2, v2, v4
	v_add_f32_e32 v3, v3, v5
	v_add_f32_e32 v6, v6, v8
	v_add_f32_e32 v7, v7, v9
	v_add_f32_e32 v2, v2, v3
	v_add_f32_e32 v3, v6, v7
	v_add_f32_e32 v5, v2, v3
	s_addk_i32 s11, 0x4000
	s_addk_i32 s12, 0x400
	v_fmac_f32_e32 v5, v51, v39
	s_cmp_eq_u32 s15, s10
	v_add_u32_e32 v46, 64, v46
	s_barrier
	s_cbranch_scc0 .LBB0_3829
	v_lshrrev_b32_e32 v4, 2, v175
	v_readlane_b32 s10, v254, 19
	v_mov_b32_e32 v3, v0
	v_lshlrev_b32_e32 v1, 3, v175
	v_or_b32_e32 v185, s10, v4
	v_lshlrev_b32_e32 v2, 7, v185
	v_lshl_add_u64 v[2:3], s[70:71], 0, v[2:3]
	s_mov_b32 s53, s55
	v_and_b32_e32 v1, 24, v1
	v_lshl_add_u64 v[2:3], v[2:3], 0, s[52:53]
	v_lshlrev_b32_e32 v132, 1, v1
	v_mov_b32_e32 v133, v0
	v_lshl_add_u64 v[2:3], v[2:3], 0, v[132:133]
	global_load_dwordx4 v[102:105], v[44:45], off
	global_load_dwordx4 v[106:109], v[2:3], off
	ds_bpermute_b32 v1, v179, v5
	s_and_b64 vcc, exec, s[8:9]
	s_waitcnt vmcnt(1)
	ds_write_b128 v184, v[102:105]
	s_waitcnt vmcnt(0)
	ds_write_b128 v184, v[106:109] offset:8192
	s_cbranch_vccz .LBB0_3838
	s_mov_b32 s51, s55
	v_lshl_add_u64 v[6:7], v[42:43], 0, s[50:51]
	v_add_co_u32_e32 v6, vcc, 0x2000, v6
	s_nop 1
	v_addc_co_u32_e32 v7, vcc, 0, v7, vcc
	v_add_co_u32_e32 v2, vcc, 0x2000, v2
	s_nop 1
	v_addc_co_u32_e32 v3, vcc, 0, v3, vcc
	global_load_dwordx4 v[102:105], v[6:7], off
	global_load_dwordx4 v[106:109], v[2:3], off

.LBB0_4169:
	s_nop 3
	v_max3_f32 v1, v35, v51, v36
	v_max3_f32 v108, v52, v37, v53
	v_max3_f32 v109, v50, v34, v38
	v_max3_f32 v110, v54, v39, v55
	v_max3_f32 v1, v1, v40, v56
	v_max3_f32 v108, v108, v41, v57
	v_max3_f32 v109, v109, v42, v58
	v_max3_f32 v110, v110, v43, v59
	v_max3_f32 v1, v1, v44, v60
	v_max3_f32 v108, v108, v45, v61
	v_max3_f32 v109, v109, v46, v62
	v_max3_f32 v110, v110, v47, v63
	v_max3_f32 v1, v1, v48, v64
	v_max3_f32 v108, v108, v49, v65
	v_max3_f32 v1, v1, v108, v109
	v_max_f32_e32 v1, v1, v110
	v_mov_b32_e32 v108, v1
	s_nop 1
	v_permlane32_swap_b32_e32 v108, v1
	s_waitcnt lgkmcnt(0)
	v_max3_f32 v1, v107, v1, v108
	v_sub_f32_e32 v107, v107, v1
	v_exp_f32_e32 v107, v107
	s_nop 0
	v_cmp_eq_f32_e32 vcc, 1.0, v107
	s_cmp_eq_u64 vcc, exec
	s_cbranch_scc1 .LBB0_4173
	s_and_saveexec_b64 s[10:11], s[8:9]
	ds_write_b32 v104, v107 offset:32768
	s_or_b64 exec, exec, s[10:11]
	ds_read_b128 v[108:111], v105 offset:32864
	ds_read_b128 v[112:115], v105 offset:32832
	ds_read_b128 v[116:119], v105 offset:32800
	ds_read_b128 v[120:123], v105 offset:32768
	s_waitcnt lgkmcnt(3)
	v_mul_f32_e32 v30, v30, v108
	v_mul_f32_e32 v31, v31, v109
	s_waitcnt lgkmcnt(2)
	v_mul_f32_e32 v26, v26, v112
	v_mul_f32_e32 v27, v27, v113
	s_waitcnt lgkmcnt(1)
	v_mul_f32_e32 v22, v22, v116
	v_mul_f32_e32 v23, v23, v117
	s_waitcnt lgkmcnt(0)
	v_mul_f32_e32 v18, v18, v120
	v_mul_f32_e32 v19, v19, v121
	v_mul_f32_e32 v14, v14, v108
	v_mul_f32_e32 v15, v15, v109
	v_mul_f32_e32 v10, v10, v112
	v_mul_f32_e32 v11, v11, v113
	v_mul_f32_e32 v6, v6, v116
	v_mul_f32_e32 v7, v7, v117
	v_mul_f32_e32 v32, v32, v110
	v_mul_f32_e32 v33, v33, v111
	v_mul_f32_e32 v28, v28, v114
	v_mul_f32_e32 v29, v29, v115
	v_mul_f32_e32 v24, v24, v118
	v_mul_f32_e32 v25, v25, v119
	v_mul_f32_e32 v20, v20, v122
	v_mul_f32_e32 v21, v21, v123
	v_mul_f32_e32 v16, v16, v110
	v_mul_f32_e32 v17, v17, v111
	v_mul_f32_e32 v12, v12, v114
	v_mul_f32_e32 v13, v13, v115
	v_mul_f32_e32 v8, v8, v118
	v_mul_f32_e32 v9, v9, v119
	v_mul_f32_e32 v4, v4, v122
	v_mul_f32_e32 v5, v5, v123
	v_mul_f32_e32 v2, v2, v120
	v_mul_f32_e32 v3, v3, v121

.LBB0_4175:
	v_add_f32_e32 v62, v62, v64
	v_add_f32_e32 v63, v63, v65
	v_add_f32_e32 v58, v58, v60
	v_add_f32_e32 v59, v59, v61
	v_add_f32_e32 v46, v46, v48
	v_add_f32_e32 v47, v47, v49
	v_add_f32_e32 v48, v54, v56
	v_add_f32_e32 v49, v55, v57
	v_add_f32_e32 v42, v42, v44
	v_add_f32_e32 v43, v43, v45
	v_add_f32_e32 v44, v50, v52
	v_add_f32_e32 v45, v51, v53
	v_add_f32_e32 v38, v38, v40
	v_add_f32_e32 v39, v39, v41
	v_add_f32_e32 v34, v34, v36
	v_add_f32_e32 v35, v35, v37
	v_add_f32_e32 v36, v38, v44
	v_add_f32_e32 v37, v39, v45
	v_add_f32_e32 v38, v42, v48
	v_add_f32_e32 v39, v43, v49
	v_add_f32_e32 v40, v46, v58
	v_add_f32_e32 v41, v47, v59
	v_add_f32_e32 v34, v34, v62
	v_add_f32_e32 v35, v35, v63
	v_add_f32_e32 v38, v40, v38
	v_add_f32_e32 v39, v41, v39
	v_add_f32_e32 v34, v34, v36
	v_add_f32_e32 v35, v35, v37
	s_add_i32 s13, s13, 1
	v_add_f32_e32 v34, v34, v35
	v_add_f32_e32 v35, v38, v39
	v_add_f32_e32 v34, v34, v35
	v_fmac_f32_e32 v34, v106, v107
	s_add_i32 s14, s14, 64
	s_addk_i32 s15, 0x4000
	s_and_b64 vcc, exec, s[10:11]
	s_waitcnt lgkmcnt(0)
	s_barrier
	s_cbranch_vccz .LBB0_4165
	ds_bpermute_b32 v1, v179, v34
	s_and_saveexec_b64 s[10:11], s[8:9]
	s_cbranch_execz .LBB0_3816
	s_waitcnt lgkmcnt(0)
	v_add_f32_e32 v1, v34, v1
	ds_write_b32 v104, v1 offset:32896
	s_branch .LBB0_3816
